# input-projection tile swizzle group 2->4 row panels (both halves), on top of m8
# speedup vs baseline: 1.0112x; 1.0112x over previous
;     __device__ __forceinline__ bool next(int i, Unit& u) const { if (i > 0) return false; return base.next(round, u); }
;     __host__ __device__ bool next(int i, Unit& u) const {
;         const long L = (long)i * G + c; if (L >= nwg) return false;
;         int wgid = (int)L; { const int q = nwg / NXCD, r = nwg % NXCD, xcd = wgid % NXCD, off = wgid / NXCD; wgid = (xcd < r ? xcd * (q + 1) : r * (q + 1) + (xcd - r) * q) + off; }
;         const int nig = wgm * nN, gid = wgid / nig, fm = gid * wgm, gsz = (nM - fm) < wgm ? (nM - fm) : wgm;
;         u.pm = fm + ((wgid % nig) % gsz); u.pn = (wgid % nig) / gsz; return true;
.Lg1_redo:
	v_readlane_b32 s0, v254, 2
	s_cmpk_lt_i32 s0, 0x700
	s_cselect_b64 s[4:5], -1, 0
	s_cmpk_gt_i32 s0, 0x6ff
	v_mbcnt_lo_u32_b32 v0, -1, 0
	v_mbcnt_hi_u32_b32 v0, -1, v0
	s_cbranch_scc1 .LBB0_361
	v_readlane_b32 s2, v254, 2
	s_ashr_i32 s0, s2, 31
	s_lshr_b32 s0, s0, 29
	s_add_i32 s0, s2, s0
	s_ashr_i32 s1, s0, 3
	s_and_b32 s0, s0, -8
	s_sub_i32 s0, s2, s0
	s_cmp_lt_i32 s0, 0
	s_movk_i32 s2, 0xe1
	s_cselect_b32 s2, s2, 0xe0
	s_mul_i32 s0, s0, s2
	s_add_i32 s0, s0, s1
	s_lshr_b32 s1, s0, 3
	s_mul_i32 s1, s1, 0x2493
	s_lshr_b32 s1, s1, 16
	s_mul_i32 s2, s1, 56
	s_sub_i32 s0, s0, s2
	s_lshl_b32 s2, s1, 2
	s_and_b32 s1, s0, 3
	s_add_i32 s66, s2, s1
	s_lshr_b32 s64, s0, 2

;     __device__ __forceinline__ bool next(int i, Unit& u) const { if (i > 0) return false; return base.next(round, u); }
;     __host__ __device__ bool next(int i, Unit& u) const {
;         const long L = (long)i * G + c; if (L >= nwg) return false;
;         int wgid = (int)L; { const int q = nwg / NXCD, r = nwg % NXCD, xcd = wgid % NXCD, off = wgid / NXCD; wgid = (xcd < r ? xcd * (q + 1) : r * (q + 1) + (xcd - r) * q) + off; }
;         const int nig = wgm * nN, gid = wgid / nig, fm = gid * wgm, gsz = (nM - fm) < wgm ? (nM - fm) : wgm;
;         u.pm = fm + ((wgid % nig) % gsz); u.pn = (wgid % nig) / gsz; return true;
; template <class Epi, class Sched, bool ALIGN_EPI = false, bool SP2 = true>
; __device__ __forceinline__ void gemm_phase(PG8_LAS unsigned char* lds, const Gemm g, const Sched& S, const Epi& E, int wid) {
;     ...
;         const bool has_next = S.next(ui + 1, nxt);
.LBB0_366:
	s_add_i32 s34, s12, 1
	s_mul_i32 s4, s34, s3
	v_readlane_b32 s5, v254, 2
	s_mul_hi_i32 s2, s34, s3
	s_add_u32 s68, s4, s5
	s_addc_u32 s69, s2, s0
	v_cmp_gt_i64_e64 s[4:5], s[68:69], v[168:169]
	s_and_b64 vcc, exec, s[4:5]
	s_mov_b32 s8, s64
	s_mov_b32 s47, s66
	s_cbranch_vccnz .LBB0_368
	s_ashr_i32 s2, s68, 31
	s_lshr_b32 s2, s2, 29
	s_add_i32 s2, s68, s2
	s_ashr_i32 s6, s2, 3
	s_and_b32 s2, s2, -8
	s_sub_i32 s2, s68, s2
	s_cmp_lt_i32 s2, 0
	s_movk_i32 s7, 0xe1
	s_cselect_b32 s7, s7, 0xe0
	s_mul_i32 s2, s2, s7
	s_add_i32 s2, s2, s6
	s_lshr_b32 s6, s2, 3
	s_mul_i32 s6, s6, 0x2493
	s_lshr_b32 s6, s6, 16
	s_mul_i32 s7, s6, 56
	s_sub_i32 s2, s2, s7
	s_lshl_b32 s7, s6, 2
	s_and_b32 s6, s2, 3
	s_add_i32 s47, s7, s6
	s_lshr_b32 s8, s2, 2
	s_mov_b32 s46, s8
	s_mov_b32 s9, s47

;     __device__ __forceinline__ bool next(int i, Unit& u) const { if (i > 0) return false; return base.next(round, u); }
;     __host__ __device__ bool next(int i, Unit& u) const {
;         const long L = (long)i * G + c; if (L >= nwg) return false;
;         int wgid = (int)L; { const int q = nwg / NXCD, r = nwg % NXCD, xcd = wgid % NXCD, off = wgid / NXCD; wgid = (xcd < r ? xcd * (q + 1) : r * (q + 1) + (xcd - r) * q) + off; }
;         const int nig = wgm * nN, gid = wgid / nig, fm = gid * wgm, gsz = (nM - fm) < wgm ? (nM - fm) : wgm;
;         u.pm = fm + ((wgid % nig) % gsz); u.pn = (wgid % nig) / gsz; return true;
.LBB0_399:
	s_cmp_eq_u32 s99, 1
	s_cbranch_scc1 .LBB0_444
	s_and_b64 vcc, exec, s[14:15]
	v_mbcnt_lo_u32_b32 v0, -1, 0
	v_mbcnt_hi_u32_b32 v0, -1, v0
	s_cbranch_vccnz .LBB0_402
	v_readlane_b32 s2, v254, 2
	s_ashr_i32 s0, s2, 31
	s_lshr_b32 s0, s0, 29
	s_add_i32 s0, s2, s0
	s_ashr_i32 s1, s0, 3
	s_and_b32 s0, s0, -8
	s_sub_i32 s0, s2, s0
	s_cmp_lt_i32 s0, 0
	s_movk_i32 s2, 0xe1
	s_cselect_b32 s2, s2, 0xe0
	s_mul_i32 s0, s0, s2
	s_add_i32 s0, s0, s1
	s_lshr_b32 s1, s0, 3
	s_mul_i32 s1, s1, 0x2493
	s_lshr_b32 s1, s1, 16
	s_mul_i32 s2, s1, 56
	s_sub_i32 s0, s0, s2
	s_lshl_b32 s2, s1, 2
	s_and_b32 s1, s0, 3
	s_add_i32 s64, s2, s1
	s_lshr_b32 s66, s0, 2
	s_and_b64 vcc, exec, s[14:15]
	s_cbranch_vccz .LBB0_403

;     __device__ __forceinline__ bool next(int i, Unit& u) const { if (i > 0) return false; return base.next(round, u); }
;     __host__ __device__ bool next(int i, Unit& u) const {
;         const long L = (long)i * G + c; if (L >= nwg) return false;
;         int wgid = (int)L; { const int q = nwg / NXCD, r = nwg % NXCD, xcd = wgid % NXCD, off = wgid / NXCD; wgid = (xcd < r ? xcd * (q + 1) : r * (q + 1) + (xcd - r) * q) + off; }
;         const int nig = wgm * nN, gid = wgid / nig, fm = gid * wgm, gsz = (nM - fm) < wgm ? (nM - fm) : wgm;
;         u.pm = fm + ((wgid % nig) % gsz); u.pn = (wgid % nig) / gsz; return true;
; template <class Epi, class Sched, bool ALIGN_EPI = false, bool SP2 = true>
; __device__ __forceinline__ void gemm_phase(PG8_LAS unsigned char* lds, const Gemm g, const Sched& S, const Epi& E, int wid) {
;     ...
;         const bool has_next = S.next(ui + 1, nxt);
.LBB0_408:
	s_add_i32 s53, s53, 1
	s_mul_i32 s0, s53, s50
	s_mul_hi_u32 s1, s53, s3
	s_add_i32 s1, s1, s0
	s_mul_i32 s0, s53, s3
	v_readlane_b32 s2, v254, 2
	s_add_u32 s68, s0, s2
	s_addc_u32 s69, s1, s51
	v_cmp_gt_i64_e32 vcc, s[68:69], v[178:179]
	v_cmp_lt_i64_e64 s[0:1], s[68:69], v[252:253]
	s_mov_b32 s8, s66
	s_mov_b32 s9, s64
	s_cbranch_vccnz .LBB0_410
	s_ashr_i32 s2, s68, 31
	s_lshr_b32 s2, s2, 29
	s_add_i32 s2, s68, s2
	s_ashr_i32 s6, s2, 3
	s_and_b32 s2, s2, -8
	s_sub_i32 s2, s68, s2
	s_cmp_lt_i32 s2, 0
	s_movk_i32 s7, 0xe1
	s_cselect_b32 s7, s7, 0xe0
	s_mul_i32 s2, s2, s7
	s_add_i32 s2, s2, s6
	s_lshr_b32 s6, s2, 3
	s_mul_i32 s6, s6, 0x2493
	s_lshr_b32 s6, s6, 16
	s_mul_i32 s7, s6, 56
	s_sub_i32 s2, s2, s7
	s_lshl_b32 s7, s6, 2
	s_and_b32 s6, s2, 3
	s_add_i32 s9, s7, s6
	s_lshr_b32 s8, s2, 2
	s_mov_b32 s13, s8
	s_mov_b32 s18, s9
